# attention: each inlined LDS-DMA piece split across two MFMA gaps (<=5 non-MFMA instructions per gap, cost-weighted spacing)
# speedup vs baseline: 1.0008x; 1.0008x over previous
; #define LAS __attribute__((address_space(3)))
; __device__ __forceinline__ void attn_unit(LAS unsigned char* lds, int b, int h, int qb, const bf16_t* Q, const bf16_t* KF, const bf16_t* VT,
;                                           const float* gout, bf16_t* MIXED, int wave, int lane) {
;     ...
;             const LAS unsigned char* kb_ = lds + (kt & 1) * ABUF;
;             const LAS unsigned char* vb_ = kb_ + KT_BYTES;
;             f32x16 sacc[2];
;             __builtin_amdgcn_s_setprio(1);
; #pragma unroll
;             for (int kb = 0; kb < 2; ++kb) {
; #pragma unroll
;                 for (int i = 0; i < 16; ++i) sacc[kb][i] = 0.f;
; #pragma unroll
;                 for (int ks = 0; ks < 12; ++ks) { const bf16x8 kf = *(const LAS bf16x8*)(kb_ + (kb * 32 + l31) * KT_STRIDE + ks * 32 + hi * 16);
;                     sacc[kb] = __builtin_amdgcn_mfma_f32_32x32x16_bf16(kf, qf[ks], sacc[kb], 0, 0, 0); }
;                 __builtin_amdgcn_sched_barrier(0);
;             }
.LBB0_453:
	s_bitcmp1_b32 s85, 0
	s_cselect_b32 s56, 0xac00, 0
	s_setprio 1
	v_add_u32_e32 v107, s56, v106
	v_add_u32_e32 v114, v107, v113
	ds_read_b128 v[224:227], v114
	ds_read_b128 v[228:231], v114 offset:32
	ds_read_b128 v[80:83], v114 offset:64
	s_waitcnt lgkmcnt(2)
	v_mfma_f32_32x32x16_bf16 v[64:79], v[224:227], v[128:131], 0
	ds_read_b128 v[224:227], v114 offset:96
	s_waitcnt lgkmcnt(2)
	v_mfma_f32_32x32x16_bf16 v[64:79], v[228:231], v[200:203], v[64:79]
	s_add_i32 m0, s81, s0
	s_and_b64 vcc, s[72:73], exec
	s_cselect_b64 s[56:57], s[62:63], s[52:53]
	ds_read_b128 v[228:231], v114 offset:128
	s_waitcnt lgkmcnt(2)
	v_mfma_f32_32x32x16_bf16 v[64:79], v[80:83], v[196:199], v[64:79]
	v_lshl_add_u64 v[232:233], v[96:97], 1, s[56:57]
	global_load_lds_dwordx4 v[232:233], off
	ds_read_b128 v[80:83], v114 offset:160
	s_waitcnt lgkmcnt(2)
	v_mfma_f32_32x32x16_bf16 v[64:79], v[224:227], v[192:195], v[64:79]
	ds_read_b128 v[224:227], v114 offset:192
	s_waitcnt lgkmcnt(2)
	v_mfma_f32_32x32x16_bf16 v[64:79], v[228:231], v[188:191], v[64:79]
	ds_read_b128 v[228:231], v114 offset:224
	s_waitcnt lgkmcnt(2)
	v_mfma_f32_32x32x16_bf16 v[64:79], v[80:83], v[184:187], v[64:79]
	s_add_i32 m0, s81, s44
	s_and_b64 vcc, s[82:83], exec
	s_cselect_b64 s[56:57], s[62:63], s[52:53]
	ds_read_b128 v[80:83], v114 offset:256
	s_waitcnt lgkmcnt(2)
	v_mfma_f32_32x32x16_bf16 v[64:79], v[224:227], v[180:183], v[64:79]
	v_lshl_add_u64 v[232:233], v[98:99], 1, s[56:57]
	global_load_lds_dwordx4 v[232:233], off
	ds_read_b128 v[224:227], v114 offset:288
	s_waitcnt lgkmcnt(2)
	v_mfma_f32_32x32x16_bf16 v[64:79], v[228:231], v[176:179], v[64:79]
	ds_read_b128 v[228:231], v114 offset:320
	s_waitcnt lgkmcnt(2)
	v_mfma_f32_32x32x16_bf16 v[64:79], v[80:83], v[172:175], v[64:79]
	ds_read_b128 v[80:83], v114 offset:352
	s_waitcnt lgkmcnt(2)
	v_mfma_f32_32x32x16_bf16 v[64:79], v[224:227], v[168:171], v[64:79]
	s_add_i32 m0, s81, s45
	s_and_b64 vcc, s[92:93], exec
	s_cselect_b64 s[56:57], s[62:63], s[52:53]
	ds_read_b128 v[224:227], v114 offset:12800
	s_waitcnt lgkmcnt(2)
	v_mfma_f32_32x32x16_bf16 v[64:79], v[228:231], v[164:167], v[64:79]
	v_lshl_add_u64 v[232:233], v[100:101], 1, s[56:57]
	global_load_lds_dwordx4 v[232:233], off
	ds_read_b128 v[228:231], v114 offset:12832
	s_waitcnt lgkmcnt(2)
	v_mfma_f32_32x32x16_bf16 v[64:79], v[80:83], v[160:163], v[64:79]
	ds_read_b128 v[108:111], v114 offset:12864
	s_waitcnt lgkmcnt(2)
	v_mfma_f32_32x32x16_bf16 v[80:95], v[224:227], v[128:131], 0
	ds_read_b128 v[224:227], v114 offset:12896
	s_waitcnt lgkmcnt(2)
	v_mfma_f32_32x32x16_bf16 v[80:95], v[228:231], v[200:203], v[80:95]
	s_add_i32 m0, s81, s1
	s_and_b64 vcc, s[66:67], exec
	s_cselect_b64 s[56:57], s[62:63], s[52:53]
	ds_read_b128 v[228:231], v114 offset:12928
	s_waitcnt lgkmcnt(2)
	v_mfma_f32_32x32x16_bf16 v[80:95], v[108:111], v[196:199], v[80:95]
	v_lshl_add_u64 v[232:233], v[102:103], 1, s[56:57]
	global_load_lds_dwordx4 v[232:233], off
	ds_read_b128 v[108:111], v114 offset:12960
	s_waitcnt lgkmcnt(2)
	v_mfma_f32_32x32x16_bf16 v[80:95], v[224:227], v[192:195], v[80:95]
	ds_read_b128 v[224:227], v114 offset:12992
	s_waitcnt lgkmcnt(2)
	v_mfma_f32_32x32x16_bf16 v[80:95], v[228:231], v[188:191], v[80:95]
	ds_read_b128 v[228:231], v114 offset:13024
	s_waitcnt lgkmcnt(2)
	v_mfma_f32_32x32x16_bf16 v[80:95], v[108:111], v[184:187], v[80:95]
	s_add_i32 m0, s81, s64
	s_and_b64 vcc, s[90:91], exec
	s_cselect_b64 s[56:57], s[62:63], s[52:53]
	ds_read_b128 v[108:111], v114 offset:13056
	s_waitcnt lgkmcnt(2)
	v_mfma_f32_32x32x16_bf16 v[80:95], v[224:227], v[180:183], v[80:95]
	v_lshl_add_u64 v[232:233], v[104:105], 1, s[56:57]
	global_load_lds_dwordx4 v[232:233], off
	ds_read_b128 v[224:227], v114 offset:13088
	s_waitcnt lgkmcnt(2)
	v_mfma_f32_32x32x16_bf16 v[80:95], v[228:231], v[176:179], v[80:95]
	ds_read_b128 v[228:231], v114 offset:13120
	s_waitcnt lgkmcnt(2)
	v_mfma_f32_32x32x16_bf16 v[80:95], v[108:111], v[172:175], v[80:95]
	ds_read_b128 v[108:111], v114 offset:13152
	s_waitcnt lgkmcnt(2)
	v_mfma_f32_32x32x16_bf16 v[80:95], v[224:227], v[168:171], v[80:95]
	s_and_b64 vcc, exec, s[14:15]
	s_cbranch_vccnz .Ldma5_skip_a
	s_add_i32 m0, s81, s65
	s_and_b64 vcc, s[78:79], exec
	s_cselect_b64 s[56:57], s[62:63], s[52:53]
	v_lshl_add_u64 v[232:233], v[206:207], 1, s[56:57]
	global_load_lds_dwordx4 v[232:233], off

; #define LAS __attribute__((address_space(3)))
; __device__ __forceinline__ void attn_unit(LAS unsigned char* lds, int b, int h, int qb, const bf16_t* Q, const bf16_t* KF, const bf16_t* VT,
;                                           const float* gout, bf16_t* MIXED, int wave, int lane) {
;     ...
;             const LAS unsigned char* kb_ = lds + (kt & 1) * ABUF;
;             const LAS unsigned char* vb_ = kb_ + KT_BYTES;
;             f32x16 sacc[2];
;             __builtin_amdgcn_s_setprio(1);
; #pragma unroll
;             for (int kb = 0; kb < 2; ++kb) {
; #pragma unroll
;                 for (int i = 0; i < 16; ++i) sacc[kb][i] = 0.f;
; #pragma unroll
;                 for (int ks = 0; ks < 12; ++ks) { const bf16x8 kf = *(const LAS bf16x8*)(kb_ + (kb * 32 + l31) * KT_STRIDE + ks * 32 + hi * 16);
;                     sacc[kb] = __builtin_amdgcn_mfma_f32_32x32x16_bf16(kf, qf[ks], sacc[kb], 0, 0, 0); }
;                 __builtin_amdgcn_sched_barrier(0);
;             }
.LBB0_506:
	s_bitcmp1_b32 s25, 0
	s_cselect_b32 s25, 0xac00, 0
	s_setprio 1
	v_add_u32_e32 v109, s25, v108
	v_add_u32_e32 v114, v109, v107
	ds_read_b128 v[224:227], v114
	ds_read_b128 v[228:231], v114 offset:32
	ds_read_b128 v[80:83], v114 offset:64
	s_waitcnt lgkmcnt(2)
	v_mfma_f32_32x32x16_bf16 v[64:79], v[224:227], v[128:131], 0
	ds_read_b128 v[224:227], v114 offset:96
	s_waitcnt lgkmcnt(2)
	v_mfma_f32_32x32x16_bf16 v[64:79], v[228:231], v[200:203], v[64:79]
	s_add_i32 m0, s23, s0
	s_and_b64 s[26:27], s[72:73], exec
	s_cselect_b64 s[26:27], s[18:19], s[16:17]
	ds_read_b128 v[228:231], v114 offset:128
	s_waitcnt lgkmcnt(2)
	v_mfma_f32_32x32x16_bf16 v[64:79], v[80:83], v[196:199], v[64:79]
	v_lshl_add_u64 v[232:233], v[96:97], 1, s[26:27]
	global_load_lds_dwordx4 v[232:233], off
	ds_read_b128 v[80:83], v114 offset:160
	s_waitcnt lgkmcnt(2)
	v_mfma_f32_32x32x16_bf16 v[64:79], v[224:227], v[192:195], v[64:79]
	ds_read_b128 v[224:227], v114 offset:192
	s_waitcnt lgkmcnt(2)
	v_mfma_f32_32x32x16_bf16 v[64:79], v[228:231], v[188:191], v[64:79]
	ds_read_b128 v[228:231], v114 offset:224
	s_waitcnt lgkmcnt(2)
	v_mfma_f32_32x32x16_bf16 v[64:79], v[80:83], v[184:187], v[64:79]
	s_add_i32 m0, s23, s44
	s_and_b64 s[26:27], s[82:83], exec
	s_cselect_b64 s[26:27], s[18:19], s[16:17]
	ds_read_b128 v[80:83], v114 offset:256
	s_waitcnt lgkmcnt(2)
	v_mfma_f32_32x32x16_bf16 v[64:79], v[224:227], v[180:183], v[64:79]
	v_lshl_add_u64 v[232:233], v[98:99], 1, s[26:27]
	global_load_lds_dwordx4 v[232:233], off
	ds_read_b128 v[224:227], v114 offset:288
	s_waitcnt lgkmcnt(2)
	v_mfma_f32_32x32x16_bf16 v[64:79], v[228:231], v[176:179], v[64:79]
	ds_read_b128 v[228:231], v114 offset:320
	s_waitcnt lgkmcnt(2)
	v_mfma_f32_32x32x16_bf16 v[64:79], v[80:83], v[172:175], v[64:79]
	ds_read_b128 v[80:83], v114 offset:352
	s_waitcnt lgkmcnt(2)
	v_mfma_f32_32x32x16_bf16 v[64:79], v[224:227], v[168:171], v[64:79]
	s_add_i32 m0, s23, s45
	s_and_b64 s[26:27], s[92:93], exec
	s_cselect_b64 s[26:27], s[18:19], s[16:17]
	ds_read_b128 v[224:227], v114 offset:12800
	s_waitcnt lgkmcnt(2)
	v_mfma_f32_32x32x16_bf16 v[64:79], v[228:231], v[164:167], v[64:79]
	v_lshl_add_u64 v[232:233], v[100:101], 1, s[26:27]
	global_load_lds_dwordx4 v[232:233], off
	ds_read_b128 v[228:231], v114 offset:12832
	s_waitcnt lgkmcnt(2)
	v_mfma_f32_32x32x16_bf16 v[64:79], v[80:83], v[160:163], v[64:79]
	ds_read_b128 v[110:113], v114 offset:12864
	s_waitcnt lgkmcnt(2)
	v_mfma_f32_32x32x16_bf16 v[80:95], v[224:227], v[128:131], 0
	ds_read_b128 v[224:227], v114 offset:12896
	s_waitcnt lgkmcnt(2)
	v_mfma_f32_32x32x16_bf16 v[80:95], v[228:231], v[200:203], v[80:95]
	s_add_i32 m0, s23, s1
	s_and_b64 s[26:27], s[66:67], exec
	s_cselect_b64 s[26:27], s[18:19], s[16:17]
	ds_read_b128 v[228:231], v114 offset:12928
	s_waitcnt lgkmcnt(2)
	v_mfma_f32_32x32x16_bf16 v[80:95], v[110:113], v[196:199], v[80:95]
	v_lshl_add_u64 v[232:233], v[102:103], 1, s[26:27]
	global_load_lds_dwordx4 v[232:233], off
	ds_read_b128 v[110:113], v114 offset:12960
	s_waitcnt lgkmcnt(2)
	v_mfma_f32_32x32x16_bf16 v[80:95], v[224:227], v[192:195], v[80:95]
	ds_read_b128 v[224:227], v114 offset:12992
	s_waitcnt lgkmcnt(2)
	v_mfma_f32_32x32x16_bf16 v[80:95], v[228:231], v[188:191], v[80:95]
	ds_read_b128 v[228:231], v114 offset:13024
	s_waitcnt lgkmcnt(2)
	v_mfma_f32_32x32x16_bf16 v[80:95], v[110:113], v[184:187], v[80:95]
	s_add_i32 m0, s23, s64
	s_and_b64 s[26:27], s[90:91], exec
	s_cselect_b64 s[26:27], s[18:19], s[16:17]
	ds_read_b128 v[110:113], v114 offset:13056
	s_waitcnt lgkmcnt(2)
	v_mfma_f32_32x32x16_bf16 v[80:95], v[224:227], v[180:183], v[80:95]
	v_lshl_add_u64 v[232:233], v[104:105], 1, s[26:27]
	global_load_lds_dwordx4 v[232:233], off
	ds_read_b128 v[224:227], v114 offset:13088
	s_waitcnt lgkmcnt(2)
	v_mfma_f32_32x32x16_bf16 v[80:95], v[228:231], v[176:179], v[80:95]
	ds_read_b128 v[228:231], v114 offset:13120
	s_waitcnt lgkmcnt(2)
	v_mfma_f32_32x32x16_bf16 v[80:95], v[110:113], v[172:175], v[80:95]
	ds_read_b128 v[110:113], v114 offset:13152
	s_waitcnt lgkmcnt(2)
	v_mfma_f32_32x32x16_bf16 v[80:95], v[224:227], v[168:171], v[80:95]
	s_and_b64 vcc, exec, s[14:15]
	s_cbranch_vccnz .Ldma5_skip_b
	s_add_i32 m0, s23, s65
	s_and_b64 s[26:27], s[78:79], exec
	s_cselect_b64 s[26:27], s[18:19], s[16:17]
	v_lshl_add_u64 v[232:233], v[206:207], 1, s[26:27]
	global_load_lds_dwordx4 v[232:233], off
